# final RMSNorm: 4 weight vectors loaded once before the row loop (no per-store vmcnt(0) chain)
# baseline (speedup 1.0000x reference)
.LBB0_10:
	s_cmp_lt_i32 s58, 7
	s_mov_b64 s[0:1], -1
	s_cbranch_scc1 .LBB0_889
	s_cmp_lt_i32 s58, 10
	s_cbranch_scc1 .LBB0_159
	s_cmp_lt_i32 s58, 12
	s_cbranch_scc1 .LBB0_27
	s_cmp_lt_i32 s58, 13
	s_cbranch_scc1 .LBB0_19
	s_cmp_eq_u32 s58, 13
	s_cbranch_scc0 .LBB0_18
	v_readlane_b32 s0, v251, 18
	v_readlane_b32 s1, v251, 19
	v_mov_b32_e32 v2, v179
	s_andn2_b64 vcc, exec, s[0:1]
	s_cbranch_vccnz .LBB0_18
	v_cmp_lt_i32_e32 vcc, v248, v221
	v_readlane_b32 s0, v251, 20
	v_readlane_b32 s1, v251, 21
	v_cndmask_b32_e32 v0, v249, v248, vcc
	v_cmp_lt_i32_e32 vcc, v220, v221
	s_load_dword s0, s[0:1], 0x0
	v_ashrrev_i32_e32 v6, 6, v2
	v_cndmask_b32_e32 v3, v249, v220, vcc
	v_cmp_lt_i32_e32 vcc, v236, v221
	v_lshlrev_b32_e32 v10, 2, v3
	v_lshlrev_b32_e32 v2, 4, v2
	v_cndmask_b32_e32 v3, v249, v236, vcc
	v_cmp_lt_i32_e32 vcc, v237, v221
	v_lshlrev_b32_e32 v11, 2, v3
	v_readlane_b32 s4, v251, 2
	v_cndmask_b32_e32 v3, v249, v237, vcc
	v_cmp_lt_i32_e32 vcc, v216, v221
	v_lshlrev_b32_e32 v12, 2, v3
	v_readlane_b32 s2, v253, 36
	v_cndmask_b32_e32 v3, v249, v216, vcc
	v_cmp_lt_i32_e32 vcc, v250, v221
	v_lshlrev_b32_e32 v13, 2, v3
	v_and_b32_e32 v4, 0x3f0, v2
	v_cndmask_b32_e32 v3, v249, v250, vcc
	v_mov_b32_e32 v5, v1
	v_readlane_b32 s14, v251, 12
	v_readlane_b32 s15, v251, 13
	v_readlane_b32 s16, v251, 14
	v_readlane_b32 s17, v251, 15
	v_readlane_b32 s1, v253, 24
	v_readlane_b32 s3, v253, 37
	v_lshlrev_b32_e32 v0, 2, v0
	s_waitcnt vmcnt(4)
	v_lshlrev_b32_e32 v14, 2, v3
	v_lshl_add_u64 v[2:3], s[14:15], 0, v[4:5]
	v_lshl_add_u64 v[4:5], s[16:17], 0, v[4:5]
	v_add_u32_e32 v6, s1, v6
	s_waitcnt lgkmcnt(0)
	s_lshl_b32 s1, s0, 3
	s_mov_b32 s3, 0x800000
	v_readlane_b32 s5, v251, 3
	v_readlane_b32 s6, v251, 4
	v_readlane_b32 s7, v251, 5
	v_readlane_b32 s8, v251, 6
	v_readlane_b32 s9, v251, 7
	v_readlane_b32 s10, v251, 8
	v_readlane_b32 s11, v251, 9
	v_readlane_b32 s12, v251, 10
	v_readlane_b32 s13, v251, 11
	v_readlane_b32 s18, v251, 16
	v_readlane_b32 s19, v251, 17
	global_load_dwordx4 v[44:47], v[2:3], off
	global_load_dwordx4 v[48:51], v[2:3], off offset:1024
	global_load_dwordx4 v[52:55], v[2:3], off offset:2048
	global_load_dwordx4 v[56:59], v[2:3], off offset:3072
.LBB0_17:
	v_ashrrev_i32_e32 v7, 31, v6
	v_lshlrev_b64 v[8:9], 12, v[6:7]
	v_lshl_add_u64 v[8:9], v[4:5], 0, v[8:9]
	global_load_dwordx4 v[16:19], v[8:9], off
	global_load_dwordx4 v[24:27], v[8:9], off offset:1024
	s_add_i32 s2, s2, s0
	v_add_u32_e32 v6, s1, v6
	s_cmpk_lt_i32 s2, 0x1000
	s_waitcnt vmcnt(1)
	v_mov_b32_e32 v30, v17
	v_mov_b32_e32 v28, v16
	s_waitcnt vmcnt(0)
	v_mov_b32_e32 v31, v25
	v_mov_b32_e32 v29, v24
	v_pk_mul_f32 v[30:31], v[30:31], v[30:31]
	v_mov_b32_e32 v32, v19
	v_pk_fma_f32 v[28:29], v[28:29], v[28:29], v[30:31]
	v_mov_b32_e32 v30, v18
	v_mov_b32_e32 v31, v26
	v_mov_b32_e32 v33, v27
	v_pk_fma_f32 v[28:29], v[30:31], v[30:31], v[28:29]
	s_nop 0
	v_pk_fma_f32 v[36:37], v[32:33], v[32:33], v[28:29]
	global_load_dwordx4 v[28:31], v[8:9], off offset:2048
	global_load_dwordx4 v[32:35], v[8:9], off offset:3072
	v_add_f32_e32 v7, v36, v37
	s_waitcnt vmcnt(1)
	v_mov_b32_e32 v40, v29
	s_waitcnt vmcnt(0)
	v_mov_b32_e32 v41, v33
	v_mov_b32_e32 v38, v28
	v_mov_b32_e32 v39, v32
	v_pk_mul_f32 v[40:41], v[40:41], v[40:41]
	v_mov_b32_e32 v42, v31
	v_pk_fma_f32 v[38:39], v[38:39], v[38:39], v[40:41]
	v_mov_b32_e32 v40, v30
	v_mov_b32_e32 v41, v34
	v_mov_b32_e32 v43, v35
	v_pk_fma_f32 v[38:39], v[40:41], v[40:41], v[38:39]
	s_nop 0
	v_pk_fma_f32 v[38:39], v[42:43], v[42:43], v[38:39]
	s_nop 0
	v_add_f32_e32 v7, v7, v38
	v_add_f32_e32 v7, v7, v39
	ds_bpermute_b32 v15, v0, v7
	s_waitcnt lgkmcnt(0)
	v_add_f32_e32 v7, v7, v15
	ds_bpermute_b32 v15, v10, v7
	s_waitcnt lgkmcnt(0)
	v_add_f32_e32 v7, v7, v15
	ds_bpermute_b32 v15, v11, v7
	s_waitcnt lgkmcnt(0)
	v_add_f32_e32 v7, v7, v15
	ds_bpermute_b32 v15, v12, v7
	s_waitcnt lgkmcnt(0)
	v_add_f32_e32 v7, v7, v15
	ds_bpermute_b32 v15, v13, v7
	s_waitcnt lgkmcnt(0)
	v_add_f32_e32 v7, v7, v15
	ds_bpermute_b32 v15, v14, v7
	s_waitcnt lgkmcnt(0)
	v_add_f32_e32 v7, v7, v15
	v_fmamk_f32 v7, v7, 0x3a800000, v178
	v_cmp_gt_f32_e32 vcc, s3, v7
	v_mul_f32_e32 v15, 0x4b800000, v7
	s_nop 0
	v_cndmask_b32_e32 v7, v7, v15, vcc
	v_rsq_f32_e32 v7, v7
	s_nop 0
	v_mul_f32_e32 v15, 0x45800000, v7
	v_cndmask_b32_e32 v36, v7, v15, vcc
	v_pk_mul_f32 v[16:17], v[16:17], v[36:37] op_sel_hi:[1,0]
	v_pk_mul_f32 v[18:19], v[18:19], v[36:37] op_sel_hi:[1,0]
	v_pk_mul_f32 v[16:17], v[44:45], v[16:17]
	v_pk_mul_f32 v[18:19], v[46:47], v[18:19]
	global_store_dwordx4 v[8:9], v[16:19], off
	v_pk_mul_f32 v[20:21], v[24:25], v[36:37] op_sel_hi:[1,0]
	v_pk_mul_f32 v[22:23], v[26:27], v[36:37] op_sel_hi:[1,0]
	v_pk_mul_f32 v[60:61], v[48:49], v[20:21]
	v_pk_mul_f32 v[62:63], v[50:51], v[22:23]
	global_store_dwordx4 v[8:9], v[60:63], off offset:1024
	v_pk_mul_f32 v[20:21], v[28:29], v[36:37] op_sel_hi:[1,0]
	v_pk_mul_f32 v[22:23], v[30:31], v[36:37] op_sel_hi:[1,0]
	v_pk_mul_f32 v[16:17], v[20:21], v[52:53]
	v_pk_mul_f32 v[18:19], v[22:23], v[54:55]
	global_store_dwordx4 v[8:9], v[16:19], off offset:2048
	v_pk_mul_f32 v[20:21], v[32:33], v[36:37] op_sel_hi:[1,0]
	v_pk_mul_f32 v[22:23], v[34:35], v[36:37] op_sel_hi:[1,0]
	v_pk_mul_f32 v[60:61], v[20:21], v[56:57]
	v_pk_mul_f32 v[62:63], v[22:23], v[58:59]
	global_store_dwordx4 v[8:9], v[60:63], off offset:3072
	s_cbranch_scc1 .LBB0_17
